# PW walks: in the first half of the hp0 value and a/k/r walks each wave issues 2-3 one-line-per-lane prefetch loads covering the RKV / v_first lines of the three later (head-pair, half) steps, so their
# speedup vs baseline: 1.0088x; 1.0088x over previous
.LBB0_661:
	s_cmp_lg_u32 s25, 0
	s_cbranch_scc1 .Lpw_pf_val_skip
	v_readfirstlane_b32 s22, v20
	v_readfirstlane_b32 s23, v21
	v_and_b32_e32 v248, 63, v0
	v_mul_u32_u24_e32 v249, 0x1800, v248
	v_add_u32_e32 v249, 0x80, v249
	v_add_u32_e32 v242, 0xffffffef, v248
	v_lshrrev_b32_e32 v243, 1, v242
	v_add_u32_e32 v243, 16, v243
	v_mul_u32_u24_e32 v243, 0x1800, v243
	v_and_b32_e32 v242, 1, v242
	v_lshl_add_u32 v243, v242, 7, v243
	v_cmp_gt_u32_e32 vcc, 17, v248
	s_nop 1
	v_cndmask_b32_e32 v249, v243, v249, vcc
	global_load_dword v241, v249, s[22:23]
	s_and_b64 vcc, exec, s[44:45]
	s_cbranch_vccnz .Lpw_pf_val_skip
	v_readfirstlane_b32 s22, v18
	v_readfirstlane_b32 s23, v19
	v_lshrrev_b32_e32 v249, 2, v248
	v_add_u32_e32 v249, 16, v249
	v_lshlrev_b32_e32 v249, 12, v249
	v_and_b32_e32 v243, 3, v248
	v_lshl_add_u32 v249, v243, 7, v249
	global_load_dword v241, v249, s[22:23]
	v_bfe_u32 v249, v248, 1, 4
	v_lshlrev_b32_e32 v249, 12, v249
	v_and_b32_e32 v243, 1, v248
	v_lshl_add_u32 v249, v243, 7, v249
	v_add_u32_e32 v249, 0x100, v249
	global_load_dword v241, v249, s[22:23]

.LBB0_751:
	s_add_i32 s22, s57, s28
	s_add_i32 s0, s22, 0xffffe000
	s_ashr_i32 s1, s0, 31
	s_add_u32 s23, s62, s0
	s_addc_u32 s44, s61, s1
	v_mad_i64_i32 v[18:19], s[0:1], s0, v216, v[130:131]
	v_mad_u64_u32 v[20:21], s[0:1], s23, v216, v[130:131]
	s_add_i32 s0, s22, 0xffffe004
	s_mulk_i32 s44, 0x1800
	s_ashr_i32 s1, s0, 31
	v_add_u32_e32 v21, s44, v21
	s_add_u32 s23, s62, s0
	global_load_dwordx2 v[46:47], v[18:19], off offset:2048
	global_load_dwordx2 v[44:45], v[20:21], off offset:2048
	global_load_dwordx2 v[48:49], v[18:19], off
	global_load_dwordx2 v[42:43], v[20:21], off
	s_addc_u32 s44, s61, s1
	v_mad_i64_i32 v[18:19], s[0:1], s0, v216, v[130:131]
	v_mad_u64_u32 v[20:21], s[0:1], s23, v216, v[130:131]
	s_add_i32 s0, s22, 0xffffe008
	s_mulk_i32 s44, 0x1800
	s_ashr_i32 s1, s0, 31
	v_add_u32_e32 v21, s44, v21
	s_add_u32 s23, s62, s0
	global_load_dwordx2 v[38:39], v[18:19], off offset:2048
	global_load_dwordx2 v[36:37], v[20:21], off offset:2048
	global_load_dwordx2 v[40:41], v[18:19], off
	global_load_dwordx2 v[34:35], v[20:21], off
	s_addc_u32 s44, s61, s1
	v_mad_i64_i32 v[18:19], s[0:1], s0, v216, v[130:131]
	v_mad_u64_u32 v[20:21], s[0:1], s23, v216, v[130:131]
	s_addk_i32 s22, 0xe00c
	s_ashr_i32 s0, s22, 31
	s_mulk_i32 s44, 0x1800
	s_add_u32 s23, s62, s22
	v_add_u32_e32 v21, s44, v21
	s_addc_u32 s44, s61, s0
	s_mulk_i32 s44, 0x1800
	v_mad_u64_u32 v[140:141], s[0:1], s23, v216, v[130:131]
	global_load_dwordx2 v[30:31], v[18:19], off offset:2048
	global_load_dwordx2 v[28:29], v[20:21], off offset:2048
	global_load_dwordx2 v[32:33], v[18:19], off
	global_load_dwordx2 v[26:27], v[20:21], off
	v_mad_i64_i32 v[18:19], s[0:1], s22, v216, v[130:131]
	v_add_u32_e32 v141, s44, v141
	global_load_dwordx2 v[22:23], v[18:19], off offset:2048
	global_load_dwordx2 v[20:21], v[140:141], off offset:2048
	global_load_dwordx2 v[24:25], v[18:19], off
	s_nop 0
	global_load_dwordx2 v[18:19], v[140:141], off
	s_cmp_lg_u32 s25, 0
	s_cbranch_scc1 .Lpw_pf_akr_skip
	v_readfirstlane_b32 s0, v140
	v_readfirstlane_b32 s1, v141
	s_sub_u32 s0, s0, 0x12000
	s_subb_u32 s1, s1, 0
	v_and_b32_e32 v248, 63, v0
	v_lshrrev_b32_e32 v249, 2, v248
	v_add_u32_e32 v249, 16, v249
	v_mul_u32_u24_e32 v249, 0x1800, v249
	v_bfe_u32 v243, v248, 1, 1
	v_lshl_add_u32 v249, v243, 11, v249
	v_and_b32_e32 v243, 1, v248
	v_lshl_add_u32 v249, v243, 7, v249
	global_load_dword v241, v249, s[0:1]
	v_lshrrev_b32_e32 v243, 1, v248
	v_mul_u32_u24_e32 v243, 0x1800, v243
	v_and_b32_e32 v242, 1, v248
	v_lshl_add_u32 v243, v242, 11, v243
	v_add_u32_e32 v243, 0x80, v243
	v_add_u32_e32 v242, 0xffffffde, v248
	v_bfe_u32 v249, v242, 1, 1
	v_lshlrev_b32_e32 v249, 11, v249
	v_and_b32_e32 v242, 1, v242
	v_lshl_add_u32 v249, v242, 7, v249
	v_add_u32_e32 v249, 0x30000, v249
	v_cmp_gt_u32_e32 vcc, 34, v248
	s_nop 1
	v_cndmask_b32_e32 v248, v249, v243, vcc
	global_load_dword v241, v248, s[0:1]
.Lpw_pf_akr_skip:
	s_mov_b64 s[0:1], -1
	s_and_b64 vcc, exec, s[20:21]
	s_cbranch_vccz .LBB0_753
	s_lshl_b64 s[0:1], s[28:29], 10
	s_add_u32 s22, s0, s2
	s_addc_u32 s23, s1, s3
	s_mov_b64 s[0:1], 0
